# DeltaNet chunkwise WY form on f32 matrix cores: decay-matrix pass fixed (lane masks formed one row ahead so no v_cndmask reads a mask the previous VALU wrote)
# baseline (speedup 1.0000x reference)
.Ldc_w3:
	s_waitcnt lgkmcnt(0)
	v_mfma_f32_16x16x4_f32 v[62:65], v66, v10, 0
	v_mfma_f32_16x16x4_f32 v[62:65], v67, v11, v[62:65]
	v_mfma_f32_16x16x4_f32 v[62:65], v68, v12, v[62:65]
	v_mfma_f32_16x16x4_f32 v[62:65], v69, v13, v[62:65]
	v_mfma_f32_16x16x4_f32 v[62:65], v70, v14, v[62:65]
	v_mfma_f32_16x16x4_f32 v[62:65], v71, v15, v[62:65]
	v_mfma_f32_16x16x4_f32 v[62:65], v72, v16, v[62:65]
	v_mfma_f32_16x16x4_f32 v[62:65], v73, v17, v[62:65]
	v_mfma_f32_16x16x4_f32 v[62:65], v74, v18, v[62:65]
	v_mfma_f32_16x16x4_f32 v[62:65], v75, v19, v[62:65]
	v_mfma_f32_16x16x4_f32 v[62:65], v76, v20, v[62:65]
	v_mfma_f32_16x16x4_f32 v[62:65], v77, v21, v[62:65]
	v_mfma_f32_16x16x4_f32 v[62:65], v78, v22, v[62:65]
	v_mfma_f32_16x16x4_f32 v[62:65], v79, v23, v[62:65]
	v_mfma_f32_16x16x4_f32 v[62:65], v80, v24, v[62:65]
	v_mfma_f32_16x16x4_f32 v[62:65], v81, v25, v[62:65]
	ds_read_b128 v[10:13], v1 offset:25600
	ds_read_b128 v[14:17], v1 offset:25616
	ds_read_b128 v[18:21], v1 offset:25632
	ds_read_b128 v[22:25], v1 offset:25648
	ds_read_b128 v[26:29], v1 offset:25664
	ds_read_b128 v[30:33], v1 offset:25680
	ds_read_b128 v[34:37], v1 offset:25696
	ds_read_b128 v[38:41], v1 offset:25712
	v_and_b32_e32 v45, 31, v221
	v_mul_u32_u24_e32 v46, 0x90, v45
	v_mov_b32_e32 v47, v45
	v_lshlrev_b32_e32 v45, 2, v45
	v_mov_b32_e32 v42, 1.0
	v_lshrrev_b32_e32 v48, 2, v221
	v_mul_u32_u24_e32 v48, 0x90, v48
	v_and_b32_e32 v49, 3, v221
	v_lshl_add_u32 v48, v49, 4, v48
	v_mov_b32_e32 v50, 0
	v_mov_b32_e32 v51, 0
	v_mov_b32_e32 v52, 0
	v_mov_b32_e32 v53, 0
	ds_write_b128 v48, v[50:53] offset:48704
	s_waitcnt lgkmcnt(0)
; __device__ __forceinline__ void dn_task(const Params& p, int l, int task, char* smem) {
;     ...
;       const float xx = ra + dtb;
;       const float sp = xx > 20.f ? xx : log1pf(__expf(xx));
;       al[t] = __expf(-Aexp * sp);
	v_cmp_ge_u32_e64 vcc, 0, v47
	v_cmp_ge_u32_e64 s[70:71], 1, v47
	v_mul_f32_e32 v43, v42, v11
	v_cndmask_b32_e64 v44, 0, v42, vcc
	ds_write_b32 v45, v44 offset:53248
	v_cndmask_b32_e64 v42, v42, v43, vcc
	v_cmp_ge_u32_e64 vcc, 2, v47
	v_mul_f32_e32 v43, v42, v12
	v_cndmask_b32_e64 v44, 0, v42, s[70:71]
	ds_write_b32 v45, v44 offset:53392
	v_cndmask_b32_e64 v42, v42, v43, s[70:71]
	v_cmp_ge_u32_e64 s[70:71], 3, v47
	v_mul_f32_e32 v43, v42, v13
	v_cndmask_b32_e64 v44, 0, v42, vcc
	ds_write_b32 v45, v44 offset:53536
	v_cndmask_b32_e64 v42, v42, v43, vcc
	v_cmp_ge_u32_e64 vcc, 4, v47
	v_mul_f32_e32 v43, v42, v14
	v_cndmask_b32_e64 v44, 0, v42, s[70:71]
	ds_write_b32 v45, v44 offset:53680
	v_cndmask_b32_e64 v42, v42, v43, s[70:71]
	v_cmp_ge_u32_e64 s[70:71], 5, v47
	v_mul_f32_e32 v43, v42, v15
	v_cndmask_b32_e64 v44, 0, v42, vcc
	ds_write_b32 v45, v44 offset:53824
	v_cndmask_b32_e64 v42, v42, v43, vcc
	v_cmp_ge_u32_e64 vcc, 6, v47
	v_mul_f32_e32 v43, v42, v16
	v_cndmask_b32_e64 v44, 0, v42, s[70:71]
	ds_write_b32 v45, v44 offset:53968
	v_cndmask_b32_e64 v42, v42, v43, s[70:71]
	v_cmp_ge_u32_e64 s[70:71], 7, v47
	v_mul_f32_e32 v43, v42, v17
	v_cndmask_b32_e64 v44, 0, v42, vcc
	ds_write_b32 v45, v44 offset:54112
	v_cndmask_b32_e64 v42, v42, v43, vcc
	v_cmp_ge_u32_e64 vcc, 8, v47
	v_mul_f32_e32 v43, v42, v18
	v_cndmask_b32_e64 v44, 0, v42, s[70:71]
	ds_write_b32 v45, v44 offset:54256
	v_cndmask_b32_e64 v42, v42, v43, s[70:71]
	v_cmp_ge_u32_e64 s[70:71], 9, v47
	v_mul_f32_e32 v43, v42, v19
	v_cndmask_b32_e64 v44, 0, v42, vcc
	ds_write_b32 v45, v44 offset:54400
	v_cndmask_b32_e64 v42, v42, v43, vcc
	v_cmp_ge_u32_e64 vcc, 10, v47
	v_mul_f32_e32 v43, v42, v20
	v_cndmask_b32_e64 v44, 0, v42, s[70:71]
	ds_write_b32 v45, v44 offset:54544
	v_cndmask_b32_e64 v42, v42, v43, s[70:71]
	v_cmp_ge_u32_e64 s[70:71], 11, v47
	v_mul_f32_e32 v43, v42, v21
	v_cndmask_b32_e64 v44, 0, v42, vcc
	ds_write_b32 v45, v44 offset:54688
	v_cndmask_b32_e64 v42, v42, v43, vcc
	v_cmp_ge_u32_e64 vcc, 12, v47
	v_mul_f32_e32 v43, v42, v22
	v_cndmask_b32_e64 v44, 0, v42, s[70:71]
	ds_write_b32 v45, v44 offset:54832
	v_cndmask_b32_e64 v42, v42, v43, s[70:71]
	v_cmp_ge_u32_e64 s[70:71], 13, v47
	v_mul_f32_e32 v43, v42, v23
	v_cndmask_b32_e64 v44, 0, v42, vcc
	ds_write_b32 v45, v44 offset:54976
	v_cndmask_b32_e64 v42, v42, v43, vcc
	v_cmp_ge_u32_e64 vcc, 14, v47
	v_mul_f32_e32 v43, v42, v24
	v_cndmask_b32_e64 v44, 0, v42, s[70:71]
	ds_write_b32 v45, v44 offset:55120
	v_cndmask_b32_e64 v42, v42, v43, s[70:71]
	v_cmp_ge_u32_e64 s[70:71], 15, v47
	v_mul_f32_e32 v43, v42, v25
	v_cndmask_b32_e64 v44, 0, v42, vcc
	ds_write_b32 v45, v44 offset:55264
	v_cndmask_b32_e64 v42, v42, v43, vcc
	v_cmp_ge_u32_e64 vcc, 16, v47
	v_mul_f32_e32 v43, v42, v26
	v_cndmask_b32_e64 v44, 0, v42, s[70:71]
	ds_write_b32 v45, v44 offset:55408
	v_cndmask_b32_e64 v42, v42, v43, s[70:71]
	v_cmp_ge_u32_e64 s[70:71], 17, v47
	v_mul_f32_e32 v43, v42, v27
	v_cndmask_b32_e64 v44, 0, v42, vcc
	ds_write_b32 v45, v44 offset:55552
	v_cndmask_b32_e64 v42, v42, v43, vcc
	v_cmp_ge_u32_e64 vcc, 18, v47
	v_mul_f32_e32 v43, v42, v28
	v_cndmask_b32_e64 v44, 0, v42, s[70:71]
	ds_write_b32 v45, v44 offset:55696
	v_cndmask_b32_e64 v42, v42, v43, s[70:71]
	v_cmp_ge_u32_e64 s[70:71], 19, v47
	v_mul_f32_e32 v43, v42, v29
	v_cndmask_b32_e64 v44, 0, v42, vcc
	ds_write_b32 v45, v44 offset:55840
	v_cndmask_b32_e64 v42, v42, v43, vcc
	v_cmp_ge_u32_e64 vcc, 20, v47
	v_mul_f32_e32 v43, v42, v30
	v_cndmask_b32_e64 v44, 0, v42, s[70:71]
	ds_write_b32 v45, v44 offset:55984
	v_cndmask_b32_e64 v42, v42, v43, s[70:71]
	v_cmp_ge_u32_e64 s[70:71], 21, v47
	v_mul_f32_e32 v43, v42, v31
	v_cndmask_b32_e64 v44, 0, v42, vcc
	ds_write_b32 v45, v44 offset:56128
	v_cndmask_b32_e64 v42, v42, v43, vcc
	v_cmp_ge_u32_e64 vcc, 22, v47
	v_mul_f32_e32 v43, v42, v32
	v_cndmask_b32_e64 v44, 0, v42, s[70:71]
	ds_write_b32 v45, v44 offset:56272
	v_cndmask_b32_e64 v42, v42, v43, s[70:71]
	v_cmp_ge_u32_e64 s[70:71], 23, v47
	v_mul_f32_e32 v43, v42, v33
	v_cndmask_b32_e64 v44, 0, v42, vcc
	ds_write_b32 v45, v44 offset:56416
	v_cndmask_b32_e64 v42, v42, v43, vcc
	v_cmp_ge_u32_e64 vcc, 24, v47
	v_mul_f32_e32 v43, v42, v34
	v_cndmask_b32_e64 v44, 0, v42, s[70:71]
	ds_write_b32 v45, v44 offset:56560
	v_cndmask_b32_e64 v42, v42, v43, s[70:71]
	v_cmp_ge_u32_e64 s[70:71], 25, v47
	v_mul_f32_e32 v43, v42, v35
	v_cndmask_b32_e64 v44, 0, v42, vcc
	ds_write_b32 v45, v44 offset:56704
	v_cndmask_b32_e64 v42, v42, v43, vcc
	v_cmp_ge_u32_e64 vcc, 26, v47
	v_mul_f32_e32 v43, v42, v36
	v_cndmask_b32_e64 v44, 0, v42, s[70:71]
	ds_write_b32 v45, v44 offset:56848
	v_cndmask_b32_e64 v42, v42, v43, s[70:71]
	v_cmp_ge_u32_e64 s[70:71], 27, v47
	v_mul_f32_e32 v43, v42, v37
	v_cndmask_b32_e64 v44, 0, v42, vcc
	ds_write_b32 v45, v44 offset:56992
	v_cndmask_b32_e64 v42, v42, v43, vcc
	v_cmp_ge_u32_e64 vcc, 28, v47
	v_mul_f32_e32 v43, v42, v38
	v_cndmask_b32_e64 v44, 0, v42, s[70:71]
	ds_write_b32 v45, v44 offset:57136
	v_cndmask_b32_e64 v42, v42, v43, s[70:71]
	v_cmp_ge_u32_e64 s[70:71], 29, v47
	v_mul_f32_e32 v43, v42, v39
	v_cndmask_b32_e64 v44, 0, v42, vcc
	ds_write_b32 v45, v44 offset:57280
	v_cndmask_b32_e64 v42, v42, v43, vcc
	v_cmp_ge_u32_e64 vcc, 30, v47
	v_mul_f32_e32 v43, v42, v40
	v_cndmask_b32_e64 v44, 0, v42, s[70:71]
	ds_write_b32 v45, v44 offset:57424
	v_cndmask_b32_e64 v42, v42, v43, s[70:71]
	v_cmp_ge_u32_e64 s[70:71], 31, v47
	v_mul_f32_e32 v43, v42, v41
	v_cndmask_b32_e64 v44, 0, v42, vcc
	ds_write_b32 v45, v44 offset:57568
	v_cndmask_b32_e64 v42, v42, v43, vcc
	s_nop 1
	v_cndmask_b32_e64 v44, 0, v42, s[70:71]
	ds_write_b32 v45, v44 offset:57712
	s_waitcnt lgkmcnt(0)
	ds_read_b32 v44, v46 offset:53248
	ds_read_b32 v43, v45 offset:57712
	s_waitcnt lgkmcnt(0)
	v_mul_f32_e32 v44, v10, v44
	v_add_u32_e32 v49, 0x13700, v45
	ds_write_b32 v49, v44
	ds_write_b32 v49, v43 offset:128
